# RWKV producers: v_rcp_f32 / v_sqrt_f32 in place of the IEEE expansions; b.r and k.r dot products as plain f32 fma chains with v_add_f32_dpp reductions
# baseline (speedup 1.0000x reference)
; #define LAS __attribute__((address_space(3)))
; template <int ph>
; __device__ __forceinline__ void run_phase(const Args& args, LAS unsigned char* lds, const int G, const int bx, const bool fin = true) {
;     ...
;                     const int tg = chunk * TC + tt0 + 16 * it; const size_t row = (size_t)b * T + tg; const bf16_t* base = PR + row * RP + chb;
;                     q_r[it] = *(const u32x2*)(base); q_k[it] = *(const u32x2*)(base + 1024); q_v[it] = *(const u32x2*)(base + 2048);
;                     if (tg > 0) { q_rp[it] = *(const u32x2*)(base - RP); q_kp[it] = *(const u32x2*)(base - RP + 1024); q_vp[it] = *(const u32x2*)(base - RP + 2048); }
;                     else { q_rp[it] = (u32x2){0u, 0u}; q_kp[it] = q_rp[it]; q_vp[it] = q_rp[it]; }
;                     q_e[it] = *(const u32x2*)(WD + row * D + chb); q_a[it] = *(const u32x2*)(AA + row * D + chb);
;                 }
;             };
;             auto derive = [&](int buf) {
;                 LAS float* V = VECb + buf * VB;
; #pragma unroll
;                 for (int it = 0; it < 2; ++it) {
;                     const int tt = tt0 + 16 * it;
;                     const f32x4 pr = unpack4(q_r[it]), pk = unpack4(q_k[it]), pv = unpack4(q_v[it]);
;                     const f32x4 r = pr + (unpack4(q_rp[it]) - pr) * mu_r, k = pk + (unpack4(q_kp[it]) - pk) * mu_k, v = pv + (unpack4(q_vp[it]) - pv) * mu_v;
;                     const f32x4 e = unpack4(q_e[it]), a = unpack4(q_a[it]);
;                     const f32x4 w = (f32x4){__expf(-e[0]), __expf(-e[1]), __expf(-e[2]), __expf(-e[3])};
;                     f32x4 kk = k * kkc; const float n2 = red16(dot4(kk, kk)); kk = kk * (1.0f / fmaxf(sqrtf(n2), 1e-12f));
;                     const f32x4 kp = k * (1.0f + (a - 1.0f) * kac), bv = kk * a, wrv = w * r;
;                     const float br = red16(dot4(bv, r)), kr = red16(dot4(kp, r));
;                     const int o = tt * 64 + 4 * cgq;
;                     *(LAS f32x4*)(V + 0 * TC * 64 + o) = -kk; *(LAS f32x4*)(V + 1 * TC * 64 + o) = wrv; *(LAS f32x4*)(V + 2 * TC * 64 + o) = w;
;                     *(LAS f32x4*)(V + 3 * TC * 64 + o) = bv; *(LAS f32x4*)(V + 4 * TC * 64 + o) = kp; *(LAS f32x4*)(V + 5 * TC * 64 + o) = v;
;                     if (cgq == 0) *(LAS f32x2*)(SCb + buf * TC * 2 + 2 * tt) = (f32x2){br, kr};
.LBB0_999:
	s_or_b64 exec, exec, s[0:1]
	v_lshlrev_b64 v[34:35], 11, v[34:35]
	v_lshl_add_u64 v[36:37], s[20:21], 0, v[34:35]
	v_lshl_add_u64 v[36:37], v[36:37], 0, v[20:21]
	global_load_dwordx2 v[38:39], v[36:37], off
	v_lshl_add_u64 v[34:35], s[22:23], 0, v[34:35]
	v_lshl_add_u64 v[34:35], v[34:35], 0, v[20:21]
	global_load_dwordx2 v[40:41], v[34:35], off
	v_or_b32_e32 v34, s42, v74
	v_mov_b64_e32 v[36:37], s[8:9]
	v_mov_b32_e32 v35, s43
	s_waitcnt vmcnt(0)
	v_lshlrev_b32_e32 v42, 16, v30
	v_and_b32_e32 v43, 0xffff0000, v30
	v_lshlrev_b32_e32 v44, 16, v26
	v_and_b32_e32 v45, 0xffff0000, v26
	v_lshlrev_b32_e32 v26, 16, v27
	v_and_b32_e32 v27, 0xffff0000, v27
	v_lshlrev_b32_e32 v46, 16, v28
	v_and_b32_e32 v47, 0xffff0000, v28
	v_lshlrev_b32_e32 v28, 16, v29
	v_and_b32_e32 v29, 0xffff0000, v29
	v_lshlrev_b32_e32 v48, 16, v32
	v_and_b32_e32 v49, 0xffff0000, v32
	v_lshlrev_b32_e32 v50, 16, v24
	v_and_b32_e32 v51, 0xffff0000, v24
	v_lshlrev_b32_e32 v52, 16, v25
	v_and_b32_e32 v53, 0xffff0000, v25
	v_lshlrev_b32_e32 v54, 16, v22
	v_and_b32_e32 v55, 0xffff0000, v22
	v_lshlrev_b32_e32 v56, 16, v23
	v_and_b32_e32 v57, 0xffff0000, v23
	v_mad_u64_u32 v[22:23], s[0:1], v34, s52, v[36:37]
	v_lshlrev_b32_e32 v30, 16, v31
	v_and_b32_e32 v31, 0xffff0000, v31
	v_lshlrev_b32_e32 v32, 16, v33
	v_and_b32_e32 v33, 0xffff0000, v33
	v_lshlrev_b64 v[24:25], 11, v[34:35]
	v_sub_f32_e32 v35, v49, v43
	v_sub_f32_e32 v34, v48, v42
	v_sub_f32_e32 v37, v51, v45
	v_sub_f32_e32 v36, v50, v44
	v_sub_f32_e32 v49, v53, v27
	v_sub_f32_e32 v48, v52, v26
	v_sub_f32_e32 v53, v57, v29
	v_sub_f32_e32 v52, v56, v28
	v_mad_i32_i24 v23, s43, v153, v23
	v_sub_f32_e32 v33, v33, v31
	v_sub_f32_e32 v32, v32, v30
	v_pk_fma_f32 v[58:59], v[12:13], v[36:37], v[44:45]
	v_pk_fma_f32 v[44:45], v[10:11], v[52:53], v[28:29]
	v_lshl_add_u64 v[28:29], v[22:23], 0, v[20:21]
	v_pk_fma_f32 v[88:89], v[18:19], v[32:33], v[30:31]
	v_add_co_u32_e32 v32, vcc, s53, v28
	v_sub_f32_e32 v51, v55, v47
	v_sub_f32_e32 v50, v54, v46
	v_lshl_add_u64 v[54:55], s[20:21], 0, v[24:25]
	v_lshl_add_u64 v[24:25], s[22:23], 0, v[24:25]
	v_addc_co_u32_e32 v33, vcc, 0, v29, vcc
	v_pk_fma_f32 v[66:67], v[16:17], v[34:35], v[42:43]
	v_pk_fma_f32 v[42:43], v[8:9], v[50:51], v[46:47]
	v_lshl_add_u64 v[22:23], v[54:55], 0, v[20:21]
	v_lshl_add_u64 v[30:31], v[24:25], 0, v[20:21]
	v_add_co_u32_e32 v46, vcc, s54, v28
	v_pk_fma_f32 v[56:57], v[14:15], v[48:49], v[26:27]
	s_nop 0
	v_addc_co_u32_e32 v47, vcc, -1, v29, vcc
	global_load_dwordx2 v[34:35], v[28:29], off
	global_load_dwordx2 v[26:27], v[28:29], off offset:-2560
	global_load_dwordx2 v[24:25], v[22:23], off
	s_nop 0
	global_load_dwordx2 v[22:23], v[30:31], off
	global_load_dwordx2 v[36:37], v[28:29], off offset:2048
	s_nop 0
	global_load_dwordx2 v[32:33], v[32:33], off
	s_nop 0
	global_load_dwordx2 v[30:31], v[46:47], off offset:-2560
	global_load_dwordx2 v[28:29], v[46:47], off offset:-512
	v_pk_mul_f32 v[54:55], v[0:1], v[58:59]
	v_pk_mul_f32 v[60:61], v[2:3], v[56:57]
	v_pk_mul_f32 v[50:51], v[54:55], v[54:55]
	v_pk_mul_f32 v[48:49], v[60:61], v[60:61]
	v_lshlrev_b32_e32 v21, 16, v38
	v_pk_mov_b32 v[52:53], v[50:51], v[48:49] op_sel:[1,0]
	v_mov_b32_e32 v51, v49
	v_mul_f32_e32 v21, 0xbfb8aa3b, v21
	v_pk_add_f32 v[48:49], v[52:53], v[50:51]
	v_exp_f32_e32 v46, v21
	v_add_f32_e32 v21, v48, v49
	v_lshlrev_b32_e32 v62, 16, v39
	v_mul_f32_e32 v49, 0xbfb8aa3b, v62
	v_add_f32_dpp v21, v21, v21 quad_perm:[1,0,3,2] row_mask:0xf bank_mask:0xf bound_ctrl:1
	v_and_b32_e32 v47, 0xffff0000, v38
	v_and_b32_e32 v63, 0xffff0000, v39
	v_add_f32_dpp v21, v21, v21 quad_perm:[2,3,0,1] row_mask:0xf bank_mask:0xf bound_ctrl:1
	v_lshlrev_b32_e32 v38, 16, v40
	v_and_b32_e32 v39, 0xffff0000, v40
	v_add_f32_dpp v21, v21, v21 row_half_mirror row_mask:0xf bank_mask:0xf bound_ctrl:1
	v_lshlrev_b32_e32 v40, 16, v41
	v_and_b32_e32 v41, 0xffff0000, v41
	v_add_f32_dpp v21, v21, v21 row_mirror row_mask:0xf bank_mask:0xf bound_ctrl:1
	v_mul_f32_e32 v47, 0xbfb8aa3b, v47
	v_exp_f32_e32 v47, v47
	v_sqrt_f32_e32 v21, v21
	s_nop 0
	v_max_f32_e32 v21, 0x2b8cbccc, v21
	s_nop 0
	v_exp_f32_e32 v48, v49
	v_mul_f32_e32 v49, 0xbfb8aa3b, v63
	v_exp_f32_e32 v49, v49
	v_rcp_f32_e32 v62, v21
	s_nop 0
	v_mul_f32_e32 v62, -1.0, v62
	v_pk_add_f32 v[50:51], v[40:41], -1.0 op_sel_hi:[1,0]
	v_pk_add_f32 v[52:53], v[38:39], -1.0 op_sel_hi:[1,0]
	v_pk_fma_f32 v[50:51], v[6:7], v[50:51], 1.0 op_sel_hi:[1,1,0]
	v_pk_fma_f32 v[64:65], v[4:5], v[52:53], 1.0 op_sel_hi:[1,1,0]
	v_pk_mul_f32 v[54:55], v[54:55], v[62:63] op_sel_hi:[1,0]
	v_pk_mul_f32 v[52:53], v[56:57], v[50:51]
	v_pk_mul_f32 v[50:51], v[58:59], v[64:65]
	v_pk_mul_f32 v[56:57], v[60:61], v[62:63] op_sel_hi:[1,0]
	v_pk_mul_f32 v[58:59], v[54:55], v[38:39] neg_lo:[1,0] neg_hi:[1,0]
	v_pk_mul_f32 v[60:61], v[56:57], v[40:41] neg_lo:[1,0] neg_hi:[1,0]
	v_mov_b32_e32 v40, v58
	v_mov_b32_e32 v41, v51
	v_pk_mov_b32 v[38:39], v[58:59], v[50:51] op_sel:[1,0]
	v_pk_mul_f32 v[40:41], v[66:67], v[40:41]
	v_pk_mul_f32 v[62:63], v[66:67], v[46:47]
	v_pk_fma_f32 v[38:39], v[66:67], v[38:39], v[40:41] op_sel:[1,0,0] op_sel_hi:[0,1,1]
	v_mov_b32_e32 v66, v60
	v_mov_b32_e32 v67, v53
	v_pk_mov_b32 v[40:41], v[60:61], v[52:53] op_sel:[1,0]
	v_pk_mul_f32 v[66:67], v[88:89], v[66:67]
	v_pk_mul_f32 v[64:65], v[88:89], v[48:49]
	v_pk_fma_f32 v[40:41], v[88:89], v[40:41], v[66:67] op_sel:[1,0,0] op_sel_hi:[0,1,1]
	v_pk_add_f32 v[38:39], v[38:39], v[40:41]
	ds_write_b128 v139, v[54:57]
	ds_write_b128 v139, v[62:65] offset:8192
	ds_write_b128 v139, v[46:49] offset:16384
	ds_write_b128 v139, v[58:61] offset:24576
	ds_write_b128 v139, v[50:53] offset:32768
	ds_write_b128 v139, v[42:45] offset:40960
	v_mov_b32_dpp v40, v38 quad_perm:[1,0,3,2] row_mask:0xf bank_mask:0xf bound_ctrl:1
	v_mov_b32_dpp v41, v39 quad_perm:[1,0,3,2] row_mask:0xf bank_mask:0xf bound_ctrl:1
	v_pk_add_f32 v[38:39], v[38:39], v[40:41]
	s_nop 1
	v_mov_b32_dpp v40, v38 quad_perm:[2,3,0,1] row_mask:0xf bank_mask:0xf bound_ctrl:1
	v_mov_b32_dpp v41, v39 quad_perm:[2,3,0,1] row_mask:0xf bank_mask:0xf bound_ctrl:1
	v_pk_add_f32 v[38:39], v[38:39], v[40:41]
	s_nop 1
	v_mov_b32_dpp v40, v38 row_half_mirror row_mask:0xf bank_mask:0xf bound_ctrl:1
	v_mov_b32_dpp v41, v39 row_half_mirror row_mask:0xf bank_mask:0xf bound_ctrl:1
	v_pk_add_f32 v[38:39], v[38:39], v[40:41]
	s_nop 1
	v_mov_b32_dpp v40, v38 row_mirror row_mask:0xf bank_mask:0xf bound_ctrl:1
	v_mov_b32_dpp v41, v39 row_mirror row_mask:0xf bank_mask:0xf bound_ctrl:1
	s_and_saveexec_b64 s[0:1], s[2:3]
	v_pk_add_f32 v[38:39], v[38:39], v[40:41]
	ds_write_b64 v140, v[38:39]
	s_or_b64 exec, exec, s[0:1]
	s_waitcnt vmcnt(7)
; __device__ __forceinline__ f32x4 unpack4(u32x2 u) { return (f32x4){__uint_as_float(u.x << 16), __uint_as_float(u.x & 0xffff0000u), __uint_as_float(u.y << 16), __uint_as_float(u.y & 0xffff0000u)}; }
; template <int ph>
; __device__ __forceinline__ void run_phase(const Args& args, LAS unsigned char* lds, const int G, const int bx, const bool fin = true) {
;     ...
;                     const f32x4 pr = unpack4(q_r[it]), pk = unpack4(q_k[it]), pv = unpack4(q_v[it]);
;                     const f32x4 r = pr + (unpack4(q_rp[it]) - pr) * mu_r, k = pk + (unpack4(q_kp[it]) - pk) * mu_k, v = pv + (unpack4(q_vp[it]) - pv) * mu_v;
	v_lshlrev_b32_e32 v38, 16, v34
	v_and_b32_e32 v39, 0xffff0000, v34
	v_lshlrev_b32_e32 v34, 16, v35
	v_and_b32_e32 v35, 0xffff0000, v35
	s_waitcnt vmcnt(1)
	v_lshlrev_b32_e32 v21, 16, v30
	v_and_b32_e32 v44, 0xffff0000, v30
	v_lshlrev_b32_e32 v30, 16, v31
	v_and_b32_e32 v31, 0xffff0000, v31
	v_sub_f32_e32 v31, v31, v35
	v_sub_f32_e32 v30, v30, v34
	v_lshlrev_b32_e32 v40, 16, v36
	v_and_b32_e32 v41, 0xffff0000, v36
	v_lshlrev_b32_e32 v36, 16, v37
	v_and_b32_e32 v37, 0xffff0000, v37
	v_sub_f32_e32 v45, v44, v39
	v_sub_f32_e32 v44, v21, v38
	v_pk_fma_f32 v[52:53], v[18:19], v[30:31], v[34:35]
	s_waitcnt vmcnt(0)
; #define LAS __attribute__((address_space(3)))
; __device__ __forceinline__ u32x2 pack4(f32x4 v) { u32x2 r; r.x = cvt_pk_bf16(v.x, v.y); r.y = cvt_pk_bf16(v.z, v.w); return r; }
; template <int ph>
; __device__ __forceinline__ void run_phase(const Args& args, LAS unsigned char* lds, const int G, const int bx, const bool fin = true) {
;     ...
;                     const f32x4 pr = unpack4(q_r[it]), pk = unpack4(q_k[it]), pv = unpack4(q_v[it]);
;                     const f32x4 r = pr + (unpack4(q_rp[it]) - pr) * mu_r, k = pk + (unpack4(q_kp[it]) - pk) * mu_k, v = pv + (unpack4(q_vp[it]) - pv) * mu_v;
;                     const f32x4 e = unpack4(q_e[it]), a = unpack4(q_a[it]);
;                     const f32x4 w = (f32x4){__expf(-e[0]), __expf(-e[1]), __expf(-e[2]), __expf(-e[3])};
;                     f32x4 kk = k * kkc; const float n2 = red16(dot4(kk, kk)); kk = kk * (1.0f / fmaxf(sqrtf(n2), 1e-12f));
;                     const f32x4 kp = k * (1.0f + (a - 1.0f) * kac), bv = kk * a, wrv = w * r;
;                     const float br = red16(dot4(bv, r)), kr = red16(dot4(kp, r));
;                     const int o = tt * 64 + 4 * cgq;
;                     *(LAS f32x4*)(V + 0 * TC * 64 + o) = -kk; *(LAS f32x4*)(V + 1 * TC * 64 + o) = wrv; *(LAS f32x4*)(V + 2 * TC * 64 + o) = w;
;                     *(LAS f32x4*)(V + 3 * TC * 64 + o) = bv; *(LAS f32x4*)(V + 4 * TC * 64 + o) = kp; *(LAS f32x4*)(V + 5 * TC * 64 + o) = v;
;                     if (cgq == 0) *(LAS f32x2*)(SCb + buf * TC * 2 + 2 * tt) = (f32x2){br, kr};
;                 }
;             };
;             auto storeY = [&](int chunk, int buf) {
;                 const int t2 = ptid >> 3, r4 = (ptid & 7) * 4;
;                 *(u32x2*)(Y + ((size_t)b * T + chunk * TC + t2) * D + h * 64 + 32 * half + r4) = pack4(*(const LAS f32x4*)(YBb + buf * TC * 32 + t2 * 32 + r4));
;             };
;             const int r8 = lane >> 3, kq = lane & 7, rowl = 8 * (wave & 3) + r8, srow = 32 * half + rowl;
;             f32x2 S0 = (f32x2){0.f, 0.f}, S1 = S0, S2 = S0, S3 = S0;
;             if (producer) {
;                 mu_r = *(const f32x4*)(shift_mu + chb); mu_k = *(const f32x4*)(shift_mu + 1024 + chb); mu_v = *(const f32x4*)(shift_mu + 2048 + chb);
;                 kkc = *(const f32x4*)(k_k + chb); kac = *(const f32x4*)(k_a + chb);
;                 issue(0); derive(0); issue(1);
	v_lshlrev_b32_e32 v21, 16, v28
	v_and_b32_e32 v28, 0xffff0000, v28
	v_lshlrev_b32_e32 v30, 16, v29
	v_and_b32_e32 v31, 0xffff0000, v29
	v_lshlrev_b32_e32 v42, 16, v32
	v_and_b32_e32 v43, 0xffff0000, v32
	v_sub_f32_e32 v29, v28, v41
	v_sub_f32_e32 v28, v21, v40
	v_sub_f32_e32 v31, v31, v37
	v_sub_f32_e32 v30, v30, v36
	v_lshlrev_b32_e32 v21, 16, v26
	v_and_b32_e32 v26, 0xffff0000, v26
	v_lshlrev_b32_e32 v32, 16, v33
	v_and_b32_e32 v33, 0xffff0000, v33
	v_pk_fma_f32 v[50:51], v[16:17], v[44:45], v[38:39]
	v_pk_fma_f32 v[34:35], v[14:15], v[30:31], v[36:37]
	v_pk_fma_f32 v[38:39], v[12:13], v[28:29], v[40:41]
	v_lshlrev_b32_e32 v28, 16, v27
	v_and_b32_e32 v29, 0xffff0000, v27
	v_sub_f32_e32 v27, v26, v43
	v_sub_f32_e32 v26, v21, v42
	v_sub_f32_e32 v29, v29, v33
	v_sub_f32_e32 v28, v28, v32
	v_pk_fma_f32 v[26:27], v[8:9], v[26:27], v[42:43]
	v_pk_mul_f32 v[42:43], v[0:1], v[38:39]
	v_pk_mul_f32 v[40:41], v[2:3], v[34:35]
	v_pk_fma_f32 v[28:29], v[10:11], v[28:29], v[32:33]
	v_pk_mul_f32 v[32:33], v[40:41], v[40:41]
	v_pk_mul_f32 v[36:37], v[42:43], v[42:43]
	v_lshlrev_b32_e32 v21, 16, v24
	v_pk_mov_b32 v[44:45], v[36:37], v[32:33] op_sel:[1,0]
	v_mov_b32_e32 v37, v33
	v_mul_f32_e32 v21, 0xbfb8aa3b, v21
	v_pk_add_f32 v[32:33], v[44:45], v[36:37]
	v_exp_f32_e32 v30, v21
	v_add_f32_e32 v21, v32, v33
	v_lshlrev_b32_e32 v46, 16, v25
	v_mul_f32_e32 v33, 0xbfb8aa3b, v46
	v_add_f32_dpp v21, v21, v21 quad_perm:[1,0,3,2] row_mask:0xf bank_mask:0xf bound_ctrl:1
	v_and_b32_e32 v31, 0xffff0000, v24
	v_and_b32_e32 v47, 0xffff0000, v25
	v_add_f32_dpp v21, v21, v21 quad_perm:[2,3,0,1] row_mask:0xf bank_mask:0xf bound_ctrl:1
	v_lshlrev_b32_e32 v24, 16, v22
	v_and_b32_e32 v25, 0xffff0000, v22
	v_add_f32_dpp v21, v21, v21 row_half_mirror row_mask:0xf bank_mask:0xf bound_ctrl:1
	v_lshlrev_b32_e32 v22, 16, v23
	v_and_b32_e32 v23, 0xffff0000, v23
	v_add_f32_dpp v21, v21, v21 row_mirror row_mask:0xf bank_mask:0xf bound_ctrl:1
	v_mul_f32_e32 v31, 0xbfb8aa3b, v31
	v_exp_f32_e32 v31, v31
	v_sqrt_f32_e32 v21, v21
	s_nop 0
	v_max_f32_e32 v21, 0x2b8cbccc, v21
	s_nop 0
	v_exp_f32_e32 v32, v33
	v_mul_f32_e32 v33, 0xbfb8aa3b, v47
	v_exp_f32_e32 v33, v33
	v_rcp_f32_e32 v46, v21
	s_nop 0
	v_mul_f32_e32 v46, -1.0, v46
	v_pk_add_f32 v[36:37], v[22:23], -1.0 op_sel_hi:[1,0]
	v_pk_add_f32 v[44:45], v[24:25], -1.0 op_sel_hi:[1,0]
	v_pk_fma_f32 v[36:37], v[6:7], v[36:37], 1.0 op_sel_hi:[1,1,0]
	v_pk_fma_f32 v[44:45], v[4:5], v[44:45], 1.0 op_sel_hi:[1,1,0]
	v_pk_mul_f32 v[36:37], v[34:35], v[36:37]
	v_pk_mul_f32 v[34:35], v[38:39], v[44:45]
	v_pk_mul_f32 v[38:39], v[42:43], v[46:47] op_sel_hi:[1,0]
	v_pk_mul_f32 v[40:41], v[40:41], v[46:47] op_sel_hi:[1,0]
	v_pk_mul_f32 v[42:43], v[38:39], v[24:25] neg_lo:[1,0] neg_hi:[1,0]
	v_mov_b32_e32 v25, v35
	v_mov_b32_e32 v24, v42
	v_pk_mul_f32 v[44:45], v[40:41], v[22:23] neg_lo:[1,0] neg_hi:[1,0]
	v_pk_mov_b32 v[22:23], v[42:43], v[34:35] op_sel:[1,0]
	v_pk_mul_f32 v[24:25], v[50:51], v[24:25]
	v_pk_mul_f32 v[46:47], v[50:51], v[30:31]
	v_pk_fma_f32 v[22:23], v[50:51], v[22:23], v[24:25] op_sel:[1,0,0] op_sel_hi:[0,1,1]
	v_mov_b32_e32 v50, v44
	v_mov_b32_e32 v51, v37
	v_pk_mov_b32 v[24:25], v[44:45], v[36:37] op_sel:[1,0]
	v_pk_mul_f32 v[50:51], v[52:53], v[50:51]
	v_pk_mul_f32 v[48:49], v[52:53], v[32:33]
	v_pk_fma_f32 v[24:25], v[52:53], v[24:25], v[50:51] op_sel:[1,0,0] op_sel_hi:[0,1,1]
	v_pk_add_f32 v[22:23], v[22:23], v[24:25]
	ds_write_b128 v142, v[38:41]
	ds_write_b128 v142, v[46:49] offset:8192
	ds_write_b128 v142, v[30:33] offset:16384
	ds_write_b128 v142, v[42:45] offset:24576
	ds_write_b128 v142, v[34:37] offset:32768
	ds_write_b128 v142, v[26:29] offset:40960
	v_mov_b32_dpp v24, v22 quad_perm:[1,0,3,2] row_mask:0xf bank_mask:0xf bound_ctrl:1
	v_mov_b32_dpp v25, v23 quad_perm:[1,0,3,2] row_mask:0xf bank_mask:0xf bound_ctrl:1
	v_pk_add_f32 v[22:23], v[22:23], v[24:25]
	s_nop 1
	v_mov_b32_dpp v24, v22 quad_perm:[2,3,0,1] row_mask:0xf bank_mask:0xf bound_ctrl:1
	v_mov_b32_dpp v25, v23 quad_perm:[2,3,0,1] row_mask:0xf bank_mask:0xf bound_ctrl:1
	v_pk_add_f32 v[22:23], v[22:23], v[24:25]
	s_nop 1
	v_mov_b32_dpp v24, v22 row_half_mirror row_mask:0xf bank_mask:0xf bound_ctrl:1
	v_mov_b32_dpp v25, v23 row_half_mirror row_mask:0xf bank_mask:0xf bound_ctrl:1
	v_pk_add_f32 v[22:23], v[22:23], v[24:25]
	s_nop 1
	v_mov_b32_dpp v24, v22 row_mirror row_mask:0xf bank_mask:0xf bound_ctrl:1
	v_mov_b32_dpp v25, v23 row_mirror row_mask:0xf bank_mask:0xf bound_ctrl:1
	s_and_saveexec_b64 s[0:1], s[2:3]
	v_pk_add_f32 v[22:23], v[22:23], v[24:25]
	ds_write_b64 v143, v[22:23]
	s_or_b64 exec, exec, s[0:1]
	v_or_b32_e32 v22, s42, v76
	v_mov_b64_e32 v[24:25], s[8:9]
	v_mad_u64_u32 v[26:27], s[0:1], v22, s52, v[24:25]
	v_mad_i32_i24 v27, s43, v153, v27
	v_mov_b32_e32 v21, v73
	v_lshl_add_u64 v[26:27], v[26:27], 0, v[20:21]
	v_add_co_u32_e32 v28, vcc, s53, v26
	v_mov_b32_e32 v23, s43
	s_nop 0
	v_addc_co_u32_e32 v29, vcc, 0, v27, vcc
	v_add_co_u32_e32 v30, vcc, s54, v26
	v_lshlrev_b64 v[22:23], 11, v[22:23]
	s_nop 0
	v_addc_co_u32_e32 v31, vcc, -1, v27, vcc
	global_load_dwordx2 v[90:91], v[26:27], off
	global_load_dwordx2 v[92:93], v[26:27], off offset:2048
	global_load_dwordx2 v[88:89], v[28:29], off
	global_load_dwordx2 v[100:101], v[26:27], off offset:-2560
	v_lshl_add_u64 v[26:27], s[20:21], 0, v[22:23]
	v_lshl_add_u64 v[22:23], s[22:23], 0, v[22:23]
	v_lshl_add_u64 v[22:23], v[22:23], 0, v[20:21]
	v_lshl_add_u64 v[26:27], v[26:27], 0, v[20:21]
	global_load_dwordx2 v[98:99], v[30:31], off offset:-2560
	global_load_dwordx2 v[96:97], v[30:31], off offset:-512
	global_load_dwordx2 v[94:95], v[26:27], off
	global_load_dwordx2 v[102:103], v[22:23], off
	v_or_b32_e32 v22, s42, v78
	v_mad_u64_u32 v[24:25], s[0:1], v22, s52, v[24:25]
	v_mad_i32_i24 v25, s43, v153, v25
	v_lshl_add_u64 v[24:25], v[24:25], 0, v[20:21]
	v_add_co_u32_e32 v26, vcc, s53, v24
	v_mov_b32_e32 v23, s43
	s_nop 0
	v_addc_co_u32_e32 v27, vcc, 0, v25, vcc
	v_add_co_u32_e32 v28, vcc, 0xfffff000, v24
	v_lshlrev_b64 v[22:23], 11, v[22:23]
	s_nop 0
	v_addc_co_u32_e32 v29, vcc, -1, v25, vcc
	global_load_dwordx2 v[108:109], v[24:25], off
	global_load_dwordx2 v[104:105], v[24:25], off offset:2048
	global_load_dwordx2 v[106:107], v[26:27], off
	global_load_dwordx2 v[110:111], v[24:25], off offset:-2560
	v_lshl_add_u64 v[24:25], s[20:21], 0, v[22:23]
	v_lshl_add_u64 v[22:23], s[22:23], 0, v[22:23]
	v_lshl_add_u64 v[24:25], v[24:25], 0, v[20:21]
	v_lshl_add_u64 v[20:21], v[22:23], 0, v[20:21]
	global_load_dwordx2 v[114:115], v[28:29], off offset:-2560
	global_load_dwordx2 v[112:113], v[28:29], off offset:-512
	global_load_dwordx2 v[118:119], v[24:25], off
	global_load_dwordx2 v[116:117], v[20:21], off

; #define LAS __attribute__((address_space(3)))
; __device__ __forceinline__ f32x4 unpack4(u32x2 u) { return (f32x4){__uint_as_float(u.x << 16), __uint_as_float(u.x & 0xffff0000u), __uint_as_float(u.y << 16), __uint_as_float(u.y & 0xffff0000u)}; }
; __device__ __forceinline__ float dot4(f32x4 a, f32x4 b) { return (a.x * b.x + a.y * b.y) + (a.z * b.z + a.w * b.w); }
; template <int ph>
; __device__ __forceinline__ void run_phase(const Args& args, LAS unsigned char* lds, const int G, const int bx, const bool fin = true) {
;     ...
;                     const f32x4 pr = unpack4(q_r[it]), pk = unpack4(q_k[it]), pv = unpack4(q_v[it]);
;                     const f32x4 r = pr + (unpack4(q_rp[it]) - pr) * mu_r, k = pk + (unpack4(q_kp[it]) - pk) * mu_k, v = pv + (unpack4(q_vp[it]) - pv) * mu_v;
;                     const f32x4 e = unpack4(q_e[it]), a = unpack4(q_a[it]);
;                     const f32x4 w = (f32x4){__expf(-e[0]), __expf(-e[1]), __expf(-e[2]), __expf(-e[3])};
;                     f32x4 kk = k * kkc; const float n2 = red16(dot4(kk, kk)); kk = kk * (1.0f / fmaxf(sqrtf(n2), 1e-12f));
;                     const f32x4 kp = k * (1.0f + (a - 1.0f) * kac), bv = kk * a, wrv = w * r;
;                     const float br = red16(dot4(bv, r)), kr = red16(dot4(kp, r));
;                     const int o = tt * 64 + 4 * cgq;
;                     *(LAS f32x4*)(V + 0 * TC * 64 + o) = -kk; *(LAS f32x4*)(V + 1 * TC * 64 + o) = wrv; *(LAS f32x4*)(V + 2 * TC * 64 + o) = w;
;                     *(LAS f32x4*)(V + 3 * TC * 64 + o) = bv; *(LAS f32x4*)(V + 4 * TC * 64 + o) = kp; *(LAS f32x4*)(V + 5 * TC * 64 + o) = v;
;                     if (cgq == 0) *(LAS f32x2*)(SCb + buf * TC * 2 + 2 * tt) = (f32x2){br, kr};
.LBB0_1014:
	s_andn2_b64 vcc, exec, s[0:1]
	s_cbranch_vccnz .LBB0_1006
	s_waitcnt vmcnt(11) lgkmcnt(5)
	v_lshlrev_b32_e32 v28, 16, v90
	v_and_b32_e32 v29, 0xffff0000, v90
	v_lshlrev_b32_e32 v30, 16, v91
	v_and_b32_e32 v31, 0xffff0000, v91
	v_lshlrev_b32_e32 v42, 16, v98
	v_and_b32_e32 v43, 0xffff0000, v98
	v_lshlrev_b32_e32 v40, 16, v99
	v_and_b32_e32 v41, 0xffff0000, v99
	v_sub_f32_e32 v41, v41, v31
	v_sub_f32_e32 v40, v40, v30
	v_sub_f32_e32 v43, v43, v29
	v_sub_f32_e32 v42, v42, v28
	s_waitcnt vmcnt(10)
	v_lshlrev_b32_e32 v32, 16, v92
	v_and_b32_e32 v33, 0xffff0000, v92
	v_lshlrev_b32_e32 v34, 16, v93
	v_and_b32_e32 v35, 0xffff0000, v93
	v_pk_fma_f32 v[28:29], v[16:17], v[42:43], v[28:29]
	v_pk_fma_f32 v[30:31], v[18:19], v[40:41], v[30:31]
	v_lshlrev_b32_e32 v40, 16, v96
	v_and_b32_e32 v41, 0xffff0000, v96
	v_lshlrev_b32_e32 v42, 16, v97
	v_and_b32_e32 v43, 0xffff0000, v97
	v_sub_f32_e32 v41, v41, v33
	v_sub_f32_e32 v40, v40, v32
	v_sub_f32_e32 v43, v43, v35
	v_sub_f32_e32 v42, v42, v34
	v_lshlrev_b32_e32 v38, 16, v89
	v_and_b32_e32 v39, 0xffff0000, v89
	v_pk_fma_f32 v[42:43], v[14:15], v[42:43], v[34:35]
	v_pk_fma_f32 v[40:41], v[12:13], v[40:41], v[32:33]
	s_waitcnt vmcnt(9)
	v_lshlrev_b32_e32 v34, 16, v101
	v_and_b32_e32 v35, 0xffff0000, v101
	v_sub_f32_e32 v35, v35, v39
	v_sub_f32_e32 v34, v34, v38
	s_waitcnt lgkmcnt(4)
	v_pk_mul_f32 v[52:53], v[0:1], v[40:41]
	s_waitcnt lgkmcnt(3)
	v_pk_mul_f32 v[46:47], v[2:3], v[42:43]
	v_pk_fma_f32 v[34:35], v[10:11], v[34:35], v[38:39]
	v_pk_mul_f32 v[38:39], v[46:47], v[46:47]
	v_pk_mul_f32 v[50:51], v[52:53], v[52:53]
	s_xor_b32 s0, s61, 1
	v_pk_mov_b32 v[54:55], v[50:51], v[38:39] op_sel:[1,0]
	v_mov_b32_e32 v51, v39
	v_pk_add_f32 v[38:39], v[54:55], v[50:51]
	s_mul_i32 s1, s0, 0xc000
	v_add_f32_e32 v38, v38, v39
	s_add_i32 s62, s1, 0
	s_lshl_b32 s61, s0, 8
	v_add_f32_dpp v38, v38, v38 quad_perm:[1,0,3,2] row_mask:0xf bank_mask:0xf bound_ctrl:1
	v_lshlrev_b32_e32 v56, 16, v95
	v_mul_f32_e32 v50, 0xbfb8aa3b, v56
	v_add_f32_dpp v38, v38, v38 quad_perm:[2,3,0,1] row_mask:0xf bank_mask:0xf bound_ctrl:1
	v_and_b32_e32 v57, 0xffff0000, v95
	v_lshlrev_b32_e32 v36, 16, v88
	v_add_f32_dpp v38, v38, v38 row_half_mirror row_mask:0xf bank_mask:0xf bound_ctrl:1
	v_and_b32_e32 v37, 0xffff0000, v88
	v_lshlrev_b32_e32 v32, 16, v100
	v_add_f32_dpp v38, v38, v38 row_mirror row_mask:0xf bank_mask:0xf bound_ctrl:1
	v_and_b32_e32 v33, 0xffff0000, v100
	v_sub_f32_e32 v33, v33, v37
	v_sub_f32_e32 v32, v32, v36
	v_pk_fma_f32 v[32:33], v[8:9], v[32:33], v[36:37]
	v_lshlrev_b32_e32 v36, 16, v94
	v_and_b32_e32 v37, 0xffff0000, v94
	s_waitcnt vmcnt(7)
	v_lshlrev_b32_e32 v44, 16, v103
	v_and_b32_e32 v45, 0xffff0000, v103
	v_mul_f32_e32 v36, 0xbfb8aa3b, v36
	v_mul_f32_e32 v37, 0xbfb8aa3b, v37
	v_sqrt_f32_e32 v38, v38
	s_nop 0
	v_max_f32_e32 v51, 0x2b8cbccc, v38
	v_exp_f32_e32 v38, v50
	v_mul_f32_e32 v39, 0xbfb8aa3b, v57
	v_lshlrev_b32_e32 v48, 16, v102
	v_and_b32_e32 v49, 0xffff0000, v102
	v_exp_f32_e32 v36, v36
	v_exp_f32_e32 v37, v37
	v_rcp_f32_e32 v54, v51
	s_nop 0
	v_mul_f32_e32 v54, -1.0, v54
	v_pk_add_f32 v[50:51], v[44:45], -1.0 op_sel_hi:[1,0]
	v_pk_add_f32 v[56:57], v[48:49], -1.0 op_sel_hi:[1,0]
	v_pk_fma_f32 v[50:51], v[6:7], v[50:51], 1.0 op_sel_hi:[1,1,0]
	v_pk_mul_f32 v[46:47], v[46:47], v[54:55] op_sel_hi:[1,0]
	v_exp_f32_e32 v39, v39
	v_pk_fma_f32 v[56:57], v[4:5], v[56:57], 1.0 op_sel_hi:[1,1,0]
	v_pk_mul_f32 v[42:43], v[50:51], v[42:43]
	v_pk_mul_f32 v[50:51], v[46:47], v[44:45] neg_lo:[1,0] neg_hi:[1,0]
	v_pk_mul_f32 v[44:45], v[52:53], v[54:55] op_sel_hi:[1,0]
	v_pk_mul_f32 v[40:41], v[56:57], v[40:41]
	v_pk_mul_f32 v[48:49], v[44:45], v[48:49] neg_lo:[1,0] neg_hi:[1,0]
	v_pk_mul_f32 v[52:53], v[36:37], v[28:29]
	v_pk_mul_f32 v[54:55], v[38:39], v[30:31]
	v_mul_f32_e32 v56, v28, v48
	v_mul_f32_e32 v57, v28, v40
	v_fmac_f32_e32 v56, v29, v49
	v_fmac_f32_e32 v57, v29, v41
	v_fmac_f32_e32 v56, v30, v50
	v_fmac_f32_e32 v57, v30, v42
	v_fmac_f32_e32 v56, v31, v51
	v_fmac_f32_e32 v57, v31, v43
	v_lshl_add_u32 v58, v138, 2, s62
	ds_write_b128 v58, v[44:47]
	ds_write_b128 v58, v[52:55] offset:8192
	ds_write_b128 v58, v[36:39] offset:16384
	ds_write_b128 v58, v[48:51] offset:24576
	ds_write_b128 v58, v[40:43] offset:32768
	ds_write_b128 v58, v[32:35] offset:40960
	v_add_f32_dpp v56, v56, v56 quad_perm:[1,0,3,2] row_mask:0xf bank_mask:0xf bound_ctrl:1
	v_add_f32_dpp v57, v57, v57 quad_perm:[1,0,3,2] row_mask:0xf bank_mask:0xf bound_ctrl:1
	s_nop 0
	v_add_f32_dpp v56, v56, v56 quad_perm:[2,3,0,1] row_mask:0xf bank_mask:0xf bound_ctrl:1
	s_nop 0
	v_add_f32_dpp v57, v57, v57 quad_perm:[2,3,0,1] row_mask:0xf bank_mask:0xf bound_ctrl:1
	s_nop 0
	v_add_f32_dpp v56, v56, v56 row_half_mirror row_mask:0xf bank_mask:0xf bound_ctrl:1
	s_nop 0
	v_add_f32_dpp v57, v57, v57 row_half_mirror row_mask:0xf bank_mask:0xf bound_ctrl:1
	s_nop 0
	v_add_f32_dpp v56, v56, v56 row_mirror row_mask:0xf bank_mask:0xf bound_ctrl:1
	s_nop 0
	v_add_f32_dpp v57, v57, v57 row_mirror row_mask:0xf bank_mask:0xf bound_ctrl:1
	s_and_saveexec_b64 s[0:1], s[2:3]
	v_add_u32_e32 v30, s61, v140
	ds_write_b64 v30, v[56:57]
	s_or_b64 exec, exec, s[0:1]
	s_waitcnt vmcnt(3)
; #define LAS __attribute__((address_space(3)))
; __device__ __forceinline__ float dot4(f32x4 a, f32x4 b) { return (a.x * b.x + a.y * b.y) + (a.z * b.z + a.w * b.w); }
; template <int ph>
; __device__ __forceinline__ void run_phase(const Args& args, LAS unsigned char* lds, const int G, const int bx, const bool fin = true) {
;     ...
;             auto issue = [&](int chunk) {
; #pragma unroll
;                 for (int it = 0; it < 2; ++it) {
;                     const int tg = chunk * TC + tt0 + 16 * it; const size_t row = (size_t)b * T + tg; const bf16_t* base = PR + row * RP + chb;
;                     q_r[it] = *(const u32x2*)(base); q_k[it] = *(const u32x2*)(base + 1024); q_v[it] = *(const u32x2*)(base + 2048);
;                     if (tg > 0) { q_rp[it] = *(const u32x2*)(base - RP); q_kp[it] = *(const u32x2*)(base - RP + 1024); q_vp[it] = *(const u32x2*)(base - RP + 2048); }
;                     else { q_rp[it] = (u32x2){0u, 0u}; q_kp[it] = q_rp[it]; q_vp[it] = q_rp[it]; }
;                     q_e[it] = *(const u32x2*)(WD + row * D + chb); q_a[it] = *(const u32x2*)(AA + row * D + chb);
;                 }
;     ...
;                     const f32x4 pr = unpack4(q_r[it]), pk = unpack4(q_k[it]), pv = unpack4(q_v[it]);
;                     const f32x4 r = pr + (unpack4(q_rp[it]) - pr) * mu_r, k = pk + (unpack4(q_kp[it]) - pk) * mu_k, v = pv + (unpack4(q_vp[it]) - pv) * mu_v;
;                     const f32x4 e = unpack4(q_e[it]), a = unpack4(q_a[it]);
;                     const f32x4 w = (f32x4){__expf(-e[0]), __expf(-e[1]), __expf(-e[2]), __expf(-e[3])};
;                     f32x4 kk = k * kkc; const float n2 = red16(dot4(kk, kk)); kk = kk * (1.0f / fmaxf(sqrtf(n2), 1e-12f));
;                     const f32x4 kp = k * (1.0f + (a - 1.0f) * kac), bv = kk * a, wrv = w * r;
;                     const float br = red16(dot4(bv, r)), kr = red16(dot4(kp, r));
;                     const int o = tt * 64 + 4 * cgq;
;                     *(LAS f32x4*)(V + 0 * TC * 64 + o) = -kk; *(LAS f32x4*)(V + 1 * TC * 64 + o) = wrv; *(LAS f32x4*)(V + 2 * TC * 64 + o) = w;
;                     *(LAS f32x4*)(V + 3 * TC * 64 + o) = bv; *(LAS f32x4*)(V + 4 * TC * 64 + o) = kp; *(LAS f32x4*)(V + 5 * TC * 64 + o) = v;
;                     if (cgq == 0) *(LAS f32x2*)(SCb + buf * TC * 2 + 2 * tt) = (f32x2){br, kr};
	v_lshlrev_b32_e32 v28, 16, v108
	v_and_b32_e32 v29, 0xffff0000, v108
	v_lshlrev_b32_e32 v30, 16, v109
	v_and_b32_e32 v31, 0xffff0000, v109
	v_lshlrev_b32_e32 v42, 16, v114
	v_and_b32_e32 v43, 0xffff0000, v114
	v_lshlrev_b32_e32 v40, 16, v115
	v_and_b32_e32 v41, 0xffff0000, v115
	v_sub_f32_e32 v41, v41, v31
	v_sub_f32_e32 v40, v40, v30
	v_sub_f32_e32 v43, v43, v29
	v_sub_f32_e32 v42, v42, v28
	v_lshlrev_b32_e32 v32, 16, v104
	v_and_b32_e32 v33, 0xffff0000, v104
	v_lshlrev_b32_e32 v34, 16, v105
	v_and_b32_e32 v35, 0xffff0000, v105
	v_pk_fma_f32 v[28:29], v[16:17], v[42:43], v[28:29]
	v_pk_fma_f32 v[30:31], v[18:19], v[40:41], v[30:31]
	v_lshlrev_b32_e32 v40, 16, v112
	v_and_b32_e32 v41, 0xffff0000, v112
	v_lshlrev_b32_e32 v42, 16, v113
	v_and_b32_e32 v43, 0xffff0000, v113
	v_sub_f32_e32 v41, v41, v33
	v_sub_f32_e32 v40, v40, v32
	v_sub_f32_e32 v43, v43, v35
	v_sub_f32_e32 v42, v42, v34
	v_lshlrev_b32_e32 v38, 16, v107
	v_and_b32_e32 v39, 0xffff0000, v107
	v_pk_fma_f32 v[42:43], v[14:15], v[42:43], v[34:35]
	v_pk_fma_f32 v[40:41], v[12:13], v[40:41], v[32:33]
	s_waitcnt vmcnt(2)
	v_lshlrev_b32_e32 v34, 16, v111
	v_and_b32_e32 v35, 0xffff0000, v111
	v_sub_f32_e32 v35, v35, v39
	v_sub_f32_e32 v34, v34, v38
	v_pk_mul_f32 v[52:53], v[0:1], v[40:41]
	v_pk_mul_f32 v[46:47], v[2:3], v[42:43]
	v_pk_fma_f32 v[34:35], v[10:11], v[34:35], v[38:39]
	v_pk_mul_f32 v[38:39], v[46:47], v[46:47]
	v_pk_mul_f32 v[50:51], v[52:53], v[52:53]
	s_waitcnt vmcnt(1)
	v_lshlrev_b32_e32 v56, 16, v119
	v_pk_mov_b32 v[54:55], v[50:51], v[38:39] op_sel:[1,0]
	v_mov_b32_e32 v51, v39
	v_pk_add_f32 v[38:39], v[54:55], v[50:51]
	v_mul_f32_e32 v50, 0xbfb8aa3b, v56
	v_add_f32_e32 v38, v38, v39
	v_and_b32_e32 v57, 0xffff0000, v119
	v_lshlrev_b32_e32 v36, 16, v106
	v_add_f32_dpp v38, v38, v38 quad_perm:[1,0,3,2] row_mask:0xf bank_mask:0xf bound_ctrl:1
	v_and_b32_e32 v37, 0xffff0000, v106
	v_lshlrev_b32_e32 v32, 16, v110
	v_add_f32_dpp v38, v38, v38 quad_perm:[2,3,0,1] row_mask:0xf bank_mask:0xf bound_ctrl:1
	v_and_b32_e32 v33, 0xffff0000, v110
	v_sub_f32_e32 v33, v33, v37
	v_add_f32_dpp v38, v38, v38 row_half_mirror row_mask:0xf bank_mask:0xf bound_ctrl:1
	v_sub_f32_e32 v32, v32, v36
	v_pk_fma_f32 v[32:33], v[8:9], v[32:33], v[36:37]
	v_add_f32_dpp v38, v38, v38 row_mirror row_mask:0xf bank_mask:0xf bound_ctrl:1
	v_lshlrev_b32_e32 v36, 16, v118
	v_and_b32_e32 v37, 0xffff0000, v118
	s_waitcnt vmcnt(0)
	v_lshlrev_b32_e32 v44, 16, v117
	v_and_b32_e32 v45, 0xffff0000, v117
	v_mul_f32_e32 v36, 0xbfb8aa3b, v36
	v_mul_f32_e32 v37, 0xbfb8aa3b, v37
	v_lshlrev_b32_e32 v48, 16, v116
	v_and_b32_e32 v49, 0xffff0000, v116
	v_exp_f32_e32 v36, v36
	v_exp_f32_e32 v37, v37
	v_sqrt_f32_e32 v38, v38
	s_nop 0
	v_max_f32_e32 v51, 0x2b8cbccc, v38
	v_exp_f32_e32 v38, v50
	v_mul_f32_e32 v39, 0xbfb8aa3b, v57
	v_exp_f32_e32 v39, v39
	v_rcp_f32_e32 v54, v51
	s_nop 0
	v_mul_f32_e32 v54, -1.0, v54
	v_pk_add_f32 v[50:51], v[44:45], -1.0 op_sel_hi:[1,0]
	v_pk_add_f32 v[56:57], v[48:49], -1.0 op_sel_hi:[1,0]
	v_pk_fma_f32 v[50:51], v[6:7], v[50:51], 1.0 op_sel_hi:[1,1,0]
	v_pk_mul_f32 v[46:47], v[46:47], v[54:55] op_sel_hi:[1,0]
	v_pk_fma_f32 v[56:57], v[4:5], v[56:57], 1.0 op_sel_hi:[1,1,0]
	v_pk_mul_f32 v[42:43], v[50:51], v[42:43]
	v_pk_mul_f32 v[50:51], v[46:47], v[44:45] neg_lo:[1,0] neg_hi:[1,0]
	v_pk_mul_f32 v[44:45], v[52:53], v[54:55] op_sel_hi:[1,0]
	v_pk_mul_f32 v[40:41], v[56:57], v[40:41]
	v_pk_mul_f32 v[48:49], v[44:45], v[48:49] neg_lo:[1,0] neg_hi:[1,0]
	v_pk_mul_f32 v[52:53], v[36:37], v[28:29]
	v_pk_mul_f32 v[54:55], v[38:39], v[30:31]
	v_mul_f32_e32 v56, v28, v48
	v_mul_f32_e32 v57, v28, v40
	v_fmac_f32_e32 v56, v29, v49
	v_fmac_f32_e32 v57, v29, v41
	v_fmac_f32_e32 v56, v30, v50
	v_fmac_f32_e32 v57, v30, v42
	v_fmac_f32_e32 v56, v31, v51
	v_fmac_f32_e32 v57, v31, v43
	v_lshl_add_u32 v58, v141, 2, s62
	ds_write_b128 v58, v[44:47]
	ds_write_b128 v58, v[52:55] offset:8192
	ds_write_b128 v58, v[36:39] offset:16384
	ds_write_b128 v58, v[48:51] offset:24576
	ds_write_b128 v58, v[40:43] offset:32768
	ds_write_b128 v58, v[32:35] offset:40960
	v_add_f32_dpp v56, v56, v56 quad_perm:[1,0,3,2] row_mask:0xf bank_mask:0xf bound_ctrl:1
	v_add_f32_dpp v57, v57, v57 quad_perm:[1,0,3,2] row_mask:0xf bank_mask:0xf bound_ctrl:1
	s_nop 0
	v_add_f32_dpp v56, v56, v56 quad_perm:[2,3,0,1] row_mask:0xf bank_mask:0xf bound_ctrl:1
	s_nop 0
	v_add_f32_dpp v57, v57, v57 quad_perm:[2,3,0,1] row_mask:0xf bank_mask:0xf bound_ctrl:1
	s_nop 0
	v_add_f32_dpp v56, v56, v56 row_half_mirror row_mask:0xf bank_mask:0xf bound_ctrl:1
	s_nop 0
	v_add_f32_dpp v57, v57, v57 row_half_mirror row_mask:0xf bank_mask:0xf bound_ctrl:1
	s_nop 0
	v_add_f32_dpp v56, v56, v56 row_mirror row_mask:0xf bank_mask:0xf bound_ctrl:1
	s_nop 0
	v_add_f32_dpp v57, v57, v57 row_mirror row_mask:0xf bank_mask:0xf bound_ctrl:1
	s_and_saveexec_b64 s[0:1], s[2:3]
	v_add_u32_e32 v30, s61, v143
	ds_write_b64 v30, v[56:57]
	s_or_b64 exec, exec, s[0:1]
	s_cmp_gt_u32 s60, 61
	s_cbranch_scc1 .LBB0_1006
	s_waitcnt lgkmcnt(14)
	v_lshl_add_u32 v72, s60, 5, v148
	v_lshl_add_u64 v[28:29], s[42:43], 0, v[72:73]
	v_mad_u64_u32 v[30:31], s[0:1], v28, s52, v[122:123]
	v_mov_b32_e32 v32, v31
	v_mad_u64_u32 v[32:33], s[0:1], v29, s52, v[32:33]
	v_add_co_u32_e32 v34, vcc, s53, v30
	v_lshlrev_b64 v[28:29], 11, v[28:29]
	s_nop 0
	v_addc_co_u32_e32 v35, vcc, 0, v32, vcc
	v_add_co_u32_e32 v36, vcc, s54, v30
	v_mov_b32_e32 v31, v32
	s_nop 0
	v_addc_co_u32_e32 v37, vcc, -1, v32, vcc
	v_lshl_add_u64 v[32:33], v[124:125], 0, v[28:29]
	v_or_b32_e32 v72, 16, v72
	global_load_dwordx2 v[88:89], v[34:35], off
	global_load_dwordx2 v[98:99], v[36:37], off offset:-2560
	global_load_dwordx2 v[96:97], v[36:37], off offset:-512
	global_load_dwordx2 v[94:95], v[32:33], off
	v_lshl_add_u64 v[32:33], s[42:43], 0, v[72:73]
	v_mad_u64_u32 v[34:35], s[0:1], v32, s52, v[122:123]
	v_mov_b32_e32 v36, v35
	v_mad_u64_u32 v[36:37], s[0:1], v33, s52, v[36:37]
	v_mov_b32_e32 v35, v36
	global_load_dwordx2 v[90:91], v[30:31], off
	global_load_dwordx2 v[92:93], v[30:31], off offset:2048
	global_load_dwordx2 v[100:101], v[30:31], off offset:-2560
	global_load_dwordx2 v[104:105], v[34:35], off offset:2048
	v_add_co_u32_e32 v30, vcc, s53, v34
	v_lshl_add_u64 v[28:29], v[126:127], 0, v[28:29]
	s_nop 0
	v_addc_co_u32_e32 v31, vcc, 0, v36, vcc
	v_add_co_u32_e32 v38, vcc, 0xfffff000, v34
	s_nop 1
	v_addc_co_u32_e32 v39, vcc, -1, v36, vcc
	global_load_dwordx2 v[102:103], v[28:29], off
	global_load_dwordx2 v[106:107], v[30:31], off
	global_load_dwordx2 v[114:115], v[38:39], off offset:-2560
	global_load_dwordx2 v[112:113], v[38:39], off offset:-512
	v_lshlrev_b64 v[28:29], 11, v[32:33]
	v_lshl_add_u64 v[30:31], v[124:125], 0, v[28:29]
	v_lshl_add_u64 v[28:29], v[126:127], 0, v[28:29]
	global_load_dwordx2 v[108:109], v[34:35], off
	global_load_dwordx2 v[110:111], v[34:35], off offset:-2560
	global_load_dwordx2 v[118:119], v[30:31], off
	global_load_dwordx2 v[116:117], v[28:29], off
	s_branch .LBB0_1006
